# xattn entry: the L1 invalidate before cross-attention is no longer waited on immediately (it completes under wave 0's in-order K-staging vmcnt waits, before the K-staged barrier that precedes the firs
# speedup vs baseline: 1.0051x; 1.0051x over previous
.LBB0_748:
	s_waitcnt vmcnt(0)
	s_waitcnt vmcnt(0) lgkmcnt(0)
	s_barrier
	s_and_saveexec_b64 s[4:5], s[90:91]
	s_cbranch_execz .LBB0_750
	buffer_inv sc1
.LBB0_750:
	s_or_b64 exec, exec, s[4:5]
	v_lshlrev_b32_e32 v148, 12, v154
	v_mov_b32_e32 v149, 0
	v_and_b32_e32 v2, 7, v223
	v_lshl_add_u64 v[0:1], s[30:31], 0, v[148:149]
	s_mov_b64 s[4:5], 0x2a00000
	s_ashr_i32 s3, s26, 31
	s_ashr_i32 s27, s2, 31
	v_lshl_add_u64 v[150:151], v[0:1], 0, s[4:5]
	v_lshlrev_b32_e32 v0, 5, v2
	v_lshlrev_b32_e32 v1, 6, v2
	v_mul_u32_u24_e32 v2, 0x230, v154
	s_add_u32 s6, s30, 0x2f00000
	s_movk_i32 s4, 0x230
	v_add3_u32 v172, 0, v1, v2
	v_or_b32_e32 v2, v178, v152
	v_and_or_b32 v3, v153, 12, v177
	s_addc_u32 s7, s31, 0
	v_lshlrev_b32_e32 v177, 1, v3
	v_mad_u32_u24 v2, v2, s4, 0
	v_mov_b32_e32 v181, v149
	v_mul_u32_u24_e32 v1, 0x230, v176
	s_add_u32 s12, s30, 0xa000000
	v_add_u32_e32 v186, v2, v177
	v_add_u32_e32 v187, 0x10680, v2
	v_add_u32_e32 v188, 0x11800, v2
	v_add_u32_e32 v189, 0x12980, v2
	v_add_u32_e32 v190, 0x13b00, v2
	v_add_u32_e32 v191, 0x14c80, v2
	v_add_u32_e32 v192, 0x15e00, v2
	v_add_u32_e32 v193, 0x16f80, v2
	v_add_u32_e32 v194, 0x18100, v2
	v_add_u32_e32 v195, 0x19280, v2
	v_add_u32_e32 v196, 0x1a400, v2
	v_add_u32_e32 v197, 0x1b580, v2
	v_add_u32_e32 v198, 0x1c700, v2
	v_add_u32_e32 v199, 0x1d880, v2
	v_add_u32_e32 v200, 0x1ea00, v2
	v_add_u32_e32 v201, 0x1fb80, v2
	v_add_u32_e32 v202, 0x20d00, v2
	v_add_u32_e32 v203, 0x21e80, v2
	v_lshl_add_u64 v[2:3], s[30:31], 0, v[180:181]
	s_mov_b64 s[4:5], 0x8000080
	v_lshlrev_b32_e32 v148, 1, v0
	v_mbcnt_lo_u32_b32 v0, -1, 0
	s_mov_b32 s11, 0
	v_add_u32_e32 v173, 0x11800, v172
	v_add_u32_e32 v174, 0x11810, v172
	v_add_u32_e32 v175, 0x11820, v172
	v_add_u32_e32 v179, 0x11830, v172
	v_add_u32_e32 v182, 0x1a400, v172
	v_add_u32_e32 v183, 0x1a410, v172
	v_add_u32_e32 v184, 0x1a420, v172
	v_add_u32_e32 v185, 0x1a430, v172
	s_addc_u32 s13, s31, 0
	v_or_b32_e32 v204, 64, v177
	v_or_b32_e32 v205, 0x80, v177
	v_or_b32_e32 v206, 0xc0, v177
	v_or_b32_e32 v207, 0x100, v177
	v_or_b32_e32 v208, 0x140, v177
	v_or_b32_e32 v209, 0x180, v177
	v_or_b32_e32 v210, 0x1c0, v177
	v_add3_u32 v211, v1, v180, 0
	v_lshl_add_u64 v[152:153], v[2:3], 0, s[4:5]
	s_mov_b64 s[14:15], 0x100
	v_mov_b64_e32 v[154:155], 0x100
	v_mov_b64_e32 v[156:157], 0xff
	s_mov_b64 s[16:17], 0x40000
	s_mov_b32 s34, 0x40000
	s_mov_b64 s[18:19], 0x80000
	s_mov_b32 s35, 0x80000
	s_mov_b64 s[36:37], 0xc0000
	s_mov_b32 s48, 0xc0000
	v_mov_b32_e32 v180, 0x358637bd
	s_mov_b32 s49, 0x800000
	s_mov_b32 s50, 0xff800000
	s_mov_b64 s[38:39], 0x40800
	s_mov_b64 s[40:41], 0x80800
	s_mov_b64 s[44:45], 0xc0800
	v_lshlrev_b32_e32 v158, 1, v178
	v_mbcnt_hi_u32_b32 v178, -1, v0
	s_mov_b32 s51, 0
	s_barrier
	s_branch .LBB0_752
